# reverse MLP-up column-tile (round) order so MLP-down reads the most recently written U columns first (cache reuse)
# speedup vs baseline: 1.0029x; 1.0027x over previous
; #define PG8_WAIT_V(n) asm volatile("s_waitcnt vmcnt(" #n ")" ::: "memory")
; #define PG8_BAR __builtin_amdgcn_s_barrier()
; template <class Epi, class Sched, bool ALIGN_EPI = false, bool SP2 = false>
; __device__ __forceinline__ void gemm_phase(PG8_LAS unsigned char* lds, const Gemm g, const Sched& S, const Epi& E) {
;     int tid_ = threadIdx.x; asm volatile("" : "+v"(tid_));
;     const int tid = tid_, wid = __builtin_amdgcn_readfirstlane(tid >> 6), lane = tid & 63, wr = wid >> 2, wc = wid & 3, fr = lane & 15, fq = lane >> 4;
;     const int K = g.K, nt = K / BK;
;     unsigned voffA[2], voffB[2];
; #pragma unroll
;     for (int i = 0; i < 2; ++i) { int R, C; stage_rc(tid * 16 + i * 8192, R, C); const int Rb = Epi::PERM ? ((R & ~31) + perm32(R & 31)) : R;
;         voffA[i] = (unsigned)(R * K + C) * 2u; voffB[i] = (unsigned)(Rb * K + C) * 2u; }
;     const size_t kstep = (size_t)(BK * 2);
;     const size_t hstep = (size_t)HALF * K * 2;
;     const size_t tstep = 2 * hstep;
;     const unsigned ldsw = (unsigned)wid * 1024u;
;     const int aoff = lds_byte(wr * 64 + fr, fq * 8), boff = lds_byte(wc * 32 + fr, fq * 8);
;     ...
;     Unit cur, nxt; int ui = 0;
;     if (!S.next(0, cur)) return;
;     f32x4 acc[2][2][4][2];
; #pragma unroll
;     for (int a = 0; a < 2; ++a)
; #pragma unroll
;         for (int b = 0; b < 2; ++b)
; #pragma unroll
;             for (int m = 0; m < 4; ++m)
; #pragma unroll
;                 for (int n = 0; n < 2; ++n) acc[a][b][m][n] = (f32x4){0.f, 0.f, 0.f, 0.f};
;     bf16x8 At[4][2], B0[2][2], B1[2][2];
;     const char* cA = (const char*)g.A + (size_t)cur.pm * tstep; const char* cB = (const char*)g.Bt + (size_t)cur.pn * tstep;
;     S.a_ready(cur);
;     if constexpr (SP2) {
;         PG8_STAGE(PG8_SB(0, 0), cB, voffB); PG8_STAGE(PG8_SB(0, 1), cB + hstep, voffB); PG8_STAGE(PG8_SA(0, 0), cA, voffA); PG8_STAGE(PG8_SA(0, 1), cA + hstep, voffA);
;         if (wr == 1) PG8_BAR;
;         PG8_WAIT_V(2); PG8_BAR;
;         PG8_STAGE(PG8_SB(1, 0), cB + kstep, voffB); PG8_STAGE(PG8_SA(1, 0), cA + kstep, voffA); PG8_STAGE(PG8_SB(1, 1), cB + hstep + kstep, voffB);
;         PG8_WAIT_V(6); PG8_BAR;
;     } else {
;         PG8_STAGE(PG8_SB(0, 0), cB, voffB); PG8_STAGE(PG8_SA(0, 0), cA, voffA); PG8_STAGE(PG8_SB(0, 1), cB + hstep, voffB); PG8_STAGE(PG8_SA(0, 1), cA + hstep, voffA);
;         if (wr == 1) PG8_BAR;
;         PG8_WAIT_V(4); PG8_BAR;
.LBB0_673:
	s_or_b64 exec, exec, s[16:17]
	v_readlane_b32 s4, v245, 38
	s_mov_b64 s[16:17], s[72:73]
	v_mov_b32_e32 v16, v202
	v_readlane_b32 s5, v245, 39
	s_waitcnt lgkmcnt(0)
	s_barrier
	s_andn2_b64 vcc, exec, s[4:5]
	v_readfirstlane_b32 s2, v16
	s_cbranch_vccnz .LBB0_693
	v_lshlrev_b32_e32 v0, 4, v16
	v_add_u32_e32 v2, 0x2000, v0
	v_ashrrev_i32_e32 v3, 31, v2
	v_lshrrev_b32_e32 v3, 22, v3
	v_add_u32_e32 v3, v2, v3
	v_ashrrev_i32_e32 v10, 10, v3
	v_mul_i32_i24_e32 v3, 0x400, v10
	v_sub_u32_e32 v2, v2, v3
	v_lshrrev_b32_e32 v3, 4, v2
	v_bitop3_b32 v2, v3, v2, 32 bitop3:0x6c
	v_ashrrev_i32_e32 v3, 31, v2
	v_lshrrev_b32_e32 v3, 26, v3
	v_add_u32_e32 v3, v2, v3
	v_lshlrev_b32_e32 v4, 3, v10
	v_ashrrev_i32_e32 v11, 6, v3
	v_and_b32_e32 v4, -16, v4
	v_add_u32_e32 v4, v11, v4
	v_and_b32_e32 v5, 3, v11
	s_mov_b32 s7, 0xfffe0
	v_lshrrev_b32_e32 v6, 2, v4
	v_lshlrev_b32_e32 v7, 1, v4
	v_and_b32_e32 v3, 0xc0, v3
	v_and_or_b32 v5, v4, s7, v5
	v_and_b32_e32 v6, 4, v6
	v_and_b32_e32 v7, 24, v7
	v_sub_u32_e32 v2, v2, v3
	v_or3_b32 v5, v5, v6, v7
	v_lshlrev_b32_e32 v6, 5, v10
	v_ashrrev_i16_sdwa v2, v206, sext(v2) dst_sel:DWORD dst_unused:UNUSED_PAD src0_sel:DWORD src1_sel:BYTE_0
	v_and_b32_e32 v6, 32, v6
	v_bfe_i32 v12, v2, 0, 16
	v_add_lshl_u32 v2, v6, v12, 1
	v_lshl_add_u32 v142, v5, 12, v2
	v_lshl_add_u32 v144, v4, 12, v2
	v_bfe_i32 v2, v16, 27, 1
	v_lshrrev_b32_e32 v2, 22, v2
	v_add_u32_e32 v2, v0, v2
	v_and_b32_e32 v2, 0xfffffc00, v2
	v_sub_u32_e32 v0, v0, v2
	s_load_dwordx2 s[24:25], s[16:17], 0x80
	v_lshrrev_b32_e32 v2, 4, v0
	v_ashrrev_i32_e32 v3, 31, v16
	v_bitop3_b32 v0, v2, v0, 32 bitop3:0x6c
	v_lshrrev_b32_e32 v3, 26, v3
	v_ashrrev_i32_e32 v2, 31, v0
	v_add_u32_e32 v3, v16, v3
	v_lshrrev_b32_e32 v2, 26, v2
	v_ashrrev_i32_e32 v14, 6, v3
	v_add_u32_e32 v2, v0, v2
	v_lshlrev_b32_e32 v3, 3, v14
	s_waitcnt lgkmcnt(0)
	s_add_u32 s26, s24, 0x6400000
	v_ashrrev_i32_e32 v13, 6, v2
	v_and_b32_e32 v3, -16, v3
	s_addc_u32 s27, s25, 0
	v_add_u32_e32 v3, v13, v3
	s_add_u32 s28, s24, 0x2400000
	v_and_b32_e32 v4, 3, v13
	v_lshrrev_b32_e32 v5, 2, v3
	v_lshlrev_b32_e32 v6, 1, v3
	v_and_b32_e32 v2, 0xc0, v2
	s_addc_u32 s29, s25, 0
	s_ashr_i32 s4, s2, 6
	v_and_or_b32 v4, v3, s7, v4
	v_and_b32_e32 v5, 4, v5
	v_and_b32_e32 v6, 24, v6
	v_sub_u32_e32 v0, v0, v2
	s_ashr_i32 s5, s2, 8
	s_lshl_b32 s58, s4, 10
	v_or3_b32 v4, v4, v5, v6
	v_lshlrev_b32_e32 v5, 5, v14
	v_ashrrev_i16_sdwa v0, v206, sext(v0) dst_sel:DWORD dst_unused:UNUSED_PAD src0_sel:DWORD src1_sel:BYTE_0
	v_readlane_b32 s8, v245, 56
	v_and_b32_e32 v5, 32, v5
	v_bfe_i32 v15, v0, 0, 16
	s_nop 0
	s_and_b32 s9, s8, 3
	s_lshl_b32 s9, s9, 1
	s_add_i32 s9, s9, 28
	s_sub_i32 s8, s9, s8
	s_lshl_b32 s8, s8, 20
	s_mov_b32 s9, 0
	s_add_u32 s18, s28, s8
	v_add_lshl_u32 v2, v5, v15, 1
	s_addc_u32 s19, s29, s9
	s_add_i32 s59, s58, 0
	v_lshl_add_u32 v0, v4, 12, v2
	s_add_i32 m0, s59, 0x10000
	v_lshl_add_u32 v146, v3, 12, v2
	global_load_lds_dwordx4 v0, s[18:19]
	s_add_i32 m0, s59, 0x12000
	s_add_u32 s8, s18, 0x80000
	global_load_lds_dwordx4 v142, s[18:19]
	s_addc_u32 s9, s19, 0
	s_add_i32 m0, s59, 0x14000
	v_mov_b32_e32 v143, v1
	global_load_lds_dwordx4 v0, s[8:9]
	s_add_i32 m0, s59, 0x16000
	v_mov_b32_e32 v147, v1
	global_load_lds_dwordx4 v142, s[8:9]
	v_readlane_b32 s8, v244, 2
	v_readlane_b32 s9, v244, 3
	s_add_u32 s16, s26, s8
	s_addc_u32 s17, s27, s9
	s_add_i32 s60, s59, 0x2000
	s_mov_b32 m0, s59
	s_add_u32 s8, s16, 0x80000
	global_load_lds_dwordx4 v146, s[16:17]
	s_mov_b32 m0, s60
	s_addc_u32 s9, s17, 0
	s_add_i32 s61, s59, 0x4000
	global_load_lds_dwordx4 v144, s[16:17]
	s_mov_b32 m0, s61
	s_add_i32 s62, s59, 0x6000
	global_load_lds_dwordx4 v146, s[8:9]
	s_mov_b32 m0, s62
	v_mov_b32_e32 v145, v1
	global_load_lds_dwordx4 v144, s[8:9]
	s_cmp_eq_u32 s5, 1
	v_lshl_add_u64 v[8:9], s[18:19], 0, v[0:1]
	v_lshl_add_u64 v[6:7], s[18:19], 0, v[142:143]
	v_lshl_add_u64 v[2:3], s[16:17], 0, v[146:147]
	s_cselect_b64 s[44:45], -1, 0
	s_cmp_lg_u32 s5, 1
	v_lshl_add_u64 v[4:5], s[16:17], 0, v[144:145]
	s_cbranch_scc1 .LBB0_676
	s_barrier
.LBB0_676:
	s_add_u32 s48, s24, 0xa400000
	s_addc_u32 s49, s25, 0
	s_lshl_b32 s7, s46, 2
	s_add_u32 s46, s24, s7
	v_lshrrev_b32_e32 v18, 1, v16
	s_addc_u32 s47, s25, 0
	v_and_b32_e32 v18, 24, v18
	s_lshl_b32 s4, s4, 5
	v_and_b32_e32 v17, 15, v16
	v_lshlrev_b32_e32 v19, 1, v18
	v_lshlrev_b32_e32 v16, 2, v16
	s_and_b32 s7, s4, 0x60
	s_add_i32 m0, s59, 0x18000
	v_lshl_add_u64 v[8:9], v[8:9], 0, s[30:31]
	v_lshl_or_b32 v162, s5, 6, v17
	v_lshl_or_b32 v17, v17, 6, v19
	s_lshl_b32 s5, s5, 13
	v_and_b32_e32 v16, 32, v16
	s_lshl_b32 s4, s7, 7
	s_waitcnt vmcnt(2)
	s_barrier
	global_load_lds_dwordx4 v[8:9], off
	v_lshl_add_u64 v[6:7], v[6:7], 0, s[30:31]
	s_add_i32 m0, s59, 0x1a000
	s_add_i32 s63, s59, 0x8000
	s_add_i32 s64, s59, 0xa000
	v_bitop3_b32 v163, v17, s4, v16 bitop3:0xde
	global_load_lds_dwordx4 v[6:7], off
	v_lshl_add_u64 v[2:3], v[2:3], 0, s[30:31]
	s_mov_b32 m0, s63
	s_add_u32 s4, s18, 0x80080
	v_bitop3_b32 v19, v17, s5, v16 bitop3:0xde
	global_load_lds_dwordx4 v[2:3], off
	v_lshl_add_u64 v[2:3], v[4:5], 0, s[30:31]
	s_mov_b32 m0, s64
	s_addc_u32 s5, s19, 0
	global_load_lds_dwordx4 v[2:3], off
	s_add_i32 m0, s59, 0x1c000
	v_lshl_add_u64 v[2:3], s[4:5], 0, v[0:1]
	global_load_lds_dwordx4 v[2:3], off
	v_lshl_add_u64 v[2:3], s[4:5], 0, v[142:143]
	s_add_i32 m0, s59, 0x1e000
	s_cmpk_lt_u32 s2, 0x100
	global_load_lds_dwordx4 v[2:3], off
	v_lshlrev_b32_e32 v2, 15, v14
	v_and_b32_e32 v2, 0xffff0000, v2
	v_lshl_add_u32 v2, v13, 12, v2
	v_and_b32_e32 v3, 1, v14
	v_lshl_or_b32 v2, v3, 6, v2
	v_lshl_add_u32 v148, v15, 1, v2
	v_lshlrev_b32_e32 v2, 15, v10
	v_and_b32_e32 v2, 0xffff0000, v2
	s_waitcnt vmcnt(6)
	v_lshl_add_u32 v2, v11, 12, v2
	v_and_b32_e32 v3, 1, v10
	v_lshl_or_b32 v2, v3, 6, v2
	s_cselect_b64 s[50:51], -1, 0
	v_or_b32_e32 v164, s7, v18
	v_mov_b32_e32 v149, v1
	v_lshl_add_u32 v150, v12, 1, v2
	v_mov_b32_e32 v151, v1
	s_mov_b32 s65, 0
	v_add_u32_e32 v165, 0, v19
	v_readlane_b32 s2, v245, 56
	v_readlane_b32 s4, v244, 0
	s_barrier
	v_readlane_b32 s5, v244, 1
	s_and_b32 s7, s2, 3
	s_lshl_b32 s7, s7, 1
	s_add_i32 s7, s7, 28
	s_sub_i32 s2, s7, s2
	s_branch .LBB0_679

;     __host__ __device__ bool next(int i, Unit& u) const {
;         const long L = (long)i * G + c; if (L >= nwg) return false;
;         int wgid = (int)L; { const int q = nwg / NXCD, r = nwg % NXCD, xcd = wgid % NXCD, off = wgid / NXCD; wgid = (xcd < r ? xcd * (q + 1) : r * (q + 1) + (xcd - r) * q) + off; }
;         const int nig = wgm * nN, gid = wgid / nig, fm = gid * wgm, gsz = (nM - fm) < wgm ? (nM - fm) : wgm;
;         u.pm = fm + ((wgid % nig) % gsz); u.pn = (wgid % nig) / gsz; return true;
.LBB0_684:
	s_ashr_i32 s5, s5, 3
	s_add_i32 s5, s8, s5
	s_ashr_i32 s7, s5, 31
	s_lshr_b32 s7, s7, 24
	s_add_i32 s7, s5, s7
	s_ashr_i32 s8, s7, 8
	s_lshl_b32 s8, s8, 3
	s_sub_i32 s9, 64, s8
	s_min_i32 s9, s9, 8
	s_abs_i32 s10, s9
	v_cvt_f32_u32_e32 v2, s10
	s_sub_i32 s12, 0, s10
	s_and_b32 s7, s7, 0xffffff00
	s_sub_i32 s5, s5, s7
	v_rcp_iflag_f32_e32 v2, v2
	s_abs_i32 s7, s5
	s_xor_b32 s11, s5, s9
	s_ashr_i32 s11, s11, 31
	v_mul_f32_e32 v2, 0x4f7ffffe, v2
	v_cvt_u32_f32_e32 v2, v2
	s_nop 0
	v_readfirstlane_b32 s13, v2
	s_mul_i32 s12, s12, s13
	s_mul_hi_u32 s12, s13, s12
	s_add_i32 s13, s13, s12
	s_mul_hi_u32 s12, s7, s13
	s_mul_i32 s13, s12, s10
	s_sub_i32 s7, s7, s13
	s_add_i32 s14, s12, 1
	s_sub_i32 s13, s7, s10
	s_cmp_ge_u32 s7, s10
	s_cselect_b32 s12, s14, s12
	s_cselect_b32 s7, s13, s7
	s_add_i32 s13, s12, 1
	s_cmp_ge_u32 s7, s10
	s_cselect_b32 s7, s13, s12
	s_xor_b32 s7, s7, s11
	s_sub_i32 s52, s7, s11
	s_mul_i32 s7, s52, s9
	s_sub_i32 s5, s5, s7
	s_add_i32 s54, s8, s5
	s_and_b32 s7, s52, 3
	s_lshl_b32 s7, s7, 1
	s_add_i32 s7, s7, 28
	s_sub_i32 s52, s7, s52
